# P0 silu(c) table fill: 36 loads in flight instead of 36 serialized round trips
# baseline (speedup 1.0000x reference)
.LBB0_11:
	s_and_b64 vcc, exec, s[6:7]
	s_cbranch_vccnz .LBB0_16
	s_and_saveexec_b64 s[6:7], s[0:1]
	s_cbranch_execz .LBB0_15
	s_mov_b32 s24, s62
	s_mov_b32 s25, s63
	global_load_dword v78, v22, s[24:25]
	global_load_dword v79, v22, s[24:25] offset:2048
	s_add_u32 s24, s24, 0x1000
	s_addc_u32 s25, s25, 0
	global_load_dword v80, v22, s[24:25]
	global_load_dword v81, v22, s[24:25] offset:2048
	s_add_u32 s24, s24, 0x1000
	s_addc_u32 s25, s25, 0
	global_load_dword v82, v22, s[24:25]
	global_load_dword v83, v22, s[24:25] offset:2048
	s_add_u32 s24, s24, 0x1000
	s_addc_u32 s25, s25, 0
	global_load_dword v84, v22, s[24:25]
	global_load_dword v85, v22, s[24:25] offset:2048
	s_add_u32 s24, s24, 0x1000
	s_addc_u32 s25, s25, 0
	global_load_dword v86, v22, s[24:25]
	global_load_dword v87, v22, s[24:25] offset:2048
	s_add_u32 s24, s24, 0x1000
	s_addc_u32 s25, s25, 0
	global_load_dword v88, v22, s[24:25]
	global_load_dword v89, v22, s[24:25] offset:2048
	s_add_u32 s24, s24, 0x1000
	s_addc_u32 s25, s25, 0
	global_load_dword v90, v22, s[24:25]
	global_load_dword v91, v22, s[24:25] offset:2048
	s_add_u32 s24, s24, 0x1000
	s_addc_u32 s25, s25, 0
	global_load_dword v92, v22, s[24:25]
	global_load_dword v93, v22, s[24:25] offset:2048
	s_add_u32 s24, s24, 0x1000
	s_addc_u32 s25, s25, 0
	global_load_dword v94, v22, s[24:25]
	global_load_dword v95, v22, s[24:25] offset:2048
	s_add_u32 s24, s24, 0x1000
	s_addc_u32 s25, s25, 0
	global_load_dword v96, v22, s[24:25]
	global_load_dword v97, v22, s[24:25] offset:2048
	s_add_u32 s24, s24, 0x1000
	s_addc_u32 s25, s25, 0
	global_load_dword v98, v22, s[24:25]
	global_load_dword v99, v22, s[24:25] offset:2048
	s_add_u32 s24, s24, 0x1000
	s_addc_u32 s25, s25, 0
	global_load_dword v100, v22, s[24:25]
	global_load_dword v101, v22, s[24:25] offset:2048
	s_add_u32 s24, s24, 0x1000
	s_addc_u32 s25, s25, 0
	global_load_dword v102, v22, s[24:25]
	global_load_dword v103, v22, s[24:25] offset:2048
	s_add_u32 s24, s24, 0x1000
	s_addc_u32 s25, s25, 0
	global_load_dword v104, v22, s[24:25]
	global_load_dword v105, v22, s[24:25] offset:2048
	s_add_u32 s24, s24, 0x1000
	s_addc_u32 s25, s25, 0
	global_load_dword v106, v22, s[24:25]
	global_load_dword v107, v22, s[24:25] offset:2048
	s_add_u32 s24, s24, 0x1000
	s_addc_u32 s25, s25, 0
	global_load_dword v108, v22, s[24:25]
	global_load_dword v109, v22, s[24:25] offset:2048
	s_mov_b32 s24, s66
	s_mov_b32 s25, s67
	global_load_dword v110, v22, s[24:25]
	global_load_dword v111, v22, s[24:25] offset:2048
	s_add_u32 s24, s24, 0x1000
	s_addc_u32 s25, s25, 0
	global_load_dword v112, v22, s[24:25]
	global_load_dword v113, v22, s[24:25] offset:2048
	v_add_u32_e32 v114, 0x10000, v22
	s_waitcnt vmcnt(0)
	v_mul_f32_e32 v115, 0xbfb8aa3b, v78
	v_mul_f32_e32 v116, 0xbfb8aa3b, v79
	v_exp_f32_e32 v115, v115
	v_exp_f32_e32 v116, v116
	s_nop 0
	v_add_f32_e32 v115, 1.0, v115
	v_add_f32_e32 v116, 1.0, v116
	v_rcp_f32_e32 v115, v115
	v_rcp_f32_e32 v116, v116
	s_nop 0
	v_mul_f32_e32 v115, v78, v115
	v_mul_f32_e32 v116, v79, v116
	ds_write_b32 v22, v115
	ds_write_b32 v22, v116 offset:2048
	v_mul_f32_e32 v115, 0xbfb8aa3b, v80
	v_mul_f32_e32 v116, 0xbfb8aa3b, v81
	v_exp_f32_e32 v115, v115
	v_exp_f32_e32 v116, v116
	s_nop 0
	v_add_f32_e32 v115, 1.0, v115
	v_add_f32_e32 v116, 1.0, v116
	v_rcp_f32_e32 v115, v115
	v_rcp_f32_e32 v116, v116
	s_nop 0
	v_mul_f32_e32 v115, v80, v115
	v_mul_f32_e32 v116, v81, v116
	ds_write_b32 v22, v115 offset:4096
	ds_write_b32 v22, v116 offset:6144
	v_mul_f32_e32 v115, 0xbfb8aa3b, v82
	v_mul_f32_e32 v116, 0xbfb8aa3b, v83
	v_exp_f32_e32 v115, v115
	v_exp_f32_e32 v116, v116
	s_nop 0
	v_add_f32_e32 v115, 1.0, v115
	v_add_f32_e32 v116, 1.0, v116
	v_rcp_f32_e32 v115, v115
	v_rcp_f32_e32 v116, v116
	s_nop 0
	v_mul_f32_e32 v115, v82, v115
	v_mul_f32_e32 v116, v83, v116
	ds_write_b32 v22, v115 offset:8192
	ds_write_b32 v22, v116 offset:10240
	v_mul_f32_e32 v115, 0xbfb8aa3b, v84
	v_mul_f32_e32 v116, 0xbfb8aa3b, v85
	v_exp_f32_e32 v115, v115
	v_exp_f32_e32 v116, v116
	s_nop 0
	v_add_f32_e32 v115, 1.0, v115
	v_add_f32_e32 v116, 1.0, v116
	v_rcp_f32_e32 v115, v115
	v_rcp_f32_e32 v116, v116
	s_nop 0
	v_mul_f32_e32 v115, v84, v115
	v_mul_f32_e32 v116, v85, v116
	ds_write_b32 v22, v115 offset:12288
	ds_write_b32 v22, v116 offset:14336
	v_mul_f32_e32 v115, 0xbfb8aa3b, v86
	v_mul_f32_e32 v116, 0xbfb8aa3b, v87
	v_exp_f32_e32 v115, v115
	v_exp_f32_e32 v116, v116
	s_nop 0
	v_add_f32_e32 v115, 1.0, v115
	v_add_f32_e32 v116, 1.0, v116
	v_rcp_f32_e32 v115, v115
	v_rcp_f32_e32 v116, v116
	s_nop 0
	v_mul_f32_e32 v115, v86, v115
	v_mul_f32_e32 v116, v87, v116
	ds_write_b32 v22, v115 offset:16384
	ds_write_b32 v22, v116 offset:18432
	v_mul_f32_e32 v115, 0xbfb8aa3b, v88
	v_mul_f32_e32 v116, 0xbfb8aa3b, v89
	v_exp_f32_e32 v115, v115
	v_exp_f32_e32 v116, v116
	s_nop 0
	v_add_f32_e32 v115, 1.0, v115
	v_add_f32_e32 v116, 1.0, v116
	v_rcp_f32_e32 v115, v115
	v_rcp_f32_e32 v116, v116
	s_nop 0
	v_mul_f32_e32 v115, v88, v115
	v_mul_f32_e32 v116, v89, v116
	ds_write_b32 v22, v115 offset:20480
	ds_write_b32 v22, v116 offset:22528
	v_mul_f32_e32 v115, 0xbfb8aa3b, v90
	v_mul_f32_e32 v116, 0xbfb8aa3b, v91
	v_exp_f32_e32 v115, v115
	v_exp_f32_e32 v116, v116
	s_nop 0
	v_add_f32_e32 v115, 1.0, v115
	v_add_f32_e32 v116, 1.0, v116
	v_rcp_f32_e32 v115, v115
	v_rcp_f32_e32 v116, v116
	s_nop 0
	v_mul_f32_e32 v115, v90, v115
	v_mul_f32_e32 v116, v91, v116
	ds_write_b32 v22, v115 offset:24576
	ds_write_b32 v22, v116 offset:26624
	v_mul_f32_e32 v115, 0xbfb8aa3b, v92
	v_mul_f32_e32 v116, 0xbfb8aa3b, v93
	v_exp_f32_e32 v115, v115
	v_exp_f32_e32 v116, v116
	s_nop 0
	v_add_f32_e32 v115, 1.0, v115
	v_add_f32_e32 v116, 1.0, v116
	v_rcp_f32_e32 v115, v115
	v_rcp_f32_e32 v116, v116
	s_nop 0
	v_mul_f32_e32 v115, v92, v115
	v_mul_f32_e32 v116, v93, v116
	ds_write_b32 v22, v115 offset:28672
	ds_write_b32 v22, v116 offset:30720
	v_mul_f32_e32 v115, 0xbfb8aa3b, v94
	v_mul_f32_e32 v116, 0xbfb8aa3b, v95
	v_exp_f32_e32 v115, v115
	v_exp_f32_e32 v116, v116
	s_nop 0
	v_add_f32_e32 v115, 1.0, v115
	v_add_f32_e32 v116, 1.0, v116
	v_rcp_f32_e32 v115, v115
	v_rcp_f32_e32 v116, v116
	s_nop 0
	v_mul_f32_e32 v115, v94, v115
	v_mul_f32_e32 v116, v95, v116
	ds_write_b32 v22, v115 offset:32768
	ds_write_b32 v22, v116 offset:34816
	v_mul_f32_e32 v115, 0xbfb8aa3b, v96
	v_mul_f32_e32 v116, 0xbfb8aa3b, v97
	v_exp_f32_e32 v115, v115
	v_exp_f32_e32 v116, v116
	s_nop 0
	v_add_f32_e32 v115, 1.0, v115
	v_add_f32_e32 v116, 1.0, v116
	v_rcp_f32_e32 v115, v115
	v_rcp_f32_e32 v116, v116
	s_nop 0
	v_mul_f32_e32 v115, v96, v115
	v_mul_f32_e32 v116, v97, v116
	ds_write_b32 v22, v115 offset:36864
	ds_write_b32 v22, v116 offset:38912
	v_mul_f32_e32 v115, 0xbfb8aa3b, v98
	v_mul_f32_e32 v116, 0xbfb8aa3b, v99
	v_exp_f32_e32 v115, v115
	v_exp_f32_e32 v116, v116
	s_nop 0
	v_add_f32_e32 v115, 1.0, v115
	v_add_f32_e32 v116, 1.0, v116
	v_rcp_f32_e32 v115, v115
	v_rcp_f32_e32 v116, v116
	s_nop 0
	v_mul_f32_e32 v115, v98, v115
	v_mul_f32_e32 v116, v99, v116
	ds_write_b32 v22, v115 offset:40960
	ds_write_b32 v22, v116 offset:43008
	v_mul_f32_e32 v115, 0xbfb8aa3b, v100
	v_mul_f32_e32 v116, 0xbfb8aa3b, v101
	v_exp_f32_e32 v115, v115
	v_exp_f32_e32 v116, v116
	s_nop 0
	v_add_f32_e32 v115, 1.0, v115
	v_add_f32_e32 v116, 1.0, v116
	v_rcp_f32_e32 v115, v115
	v_rcp_f32_e32 v116, v116
	s_nop 0
	v_mul_f32_e32 v115, v100, v115
	v_mul_f32_e32 v116, v101, v116
	ds_write_b32 v22, v115 offset:45056
	ds_write_b32 v22, v116 offset:47104
	v_mul_f32_e32 v115, 0xbfb8aa3b, v102
	v_mul_f32_e32 v116, 0xbfb8aa3b, v103
	v_exp_f32_e32 v115, v115
	v_exp_f32_e32 v116, v116
	s_nop 0
	v_add_f32_e32 v115, 1.0, v115
	v_add_f32_e32 v116, 1.0, v116
	v_rcp_f32_e32 v115, v115
	v_rcp_f32_e32 v116, v116
	s_nop 0
	v_mul_f32_e32 v115, v102, v115
	v_mul_f32_e32 v116, v103, v116
	ds_write_b32 v22, v115 offset:49152
	ds_write_b32 v22, v116 offset:51200
	v_mul_f32_e32 v115, 0xbfb8aa3b, v104
	v_mul_f32_e32 v116, 0xbfb8aa3b, v105
	v_exp_f32_e32 v115, v115
	v_exp_f32_e32 v116, v116
	s_nop 0
	v_add_f32_e32 v115, 1.0, v115
	v_add_f32_e32 v116, 1.0, v116
	v_rcp_f32_e32 v115, v115
	v_rcp_f32_e32 v116, v116
	s_nop 0
	v_mul_f32_e32 v115, v104, v115
	v_mul_f32_e32 v116, v105, v116
	ds_write_b32 v22, v115 offset:53248
	ds_write_b32 v22, v116 offset:55296
	v_mul_f32_e32 v115, 0xbfb8aa3b, v106
	v_mul_f32_e32 v116, 0xbfb8aa3b, v107
	v_exp_f32_e32 v115, v115
	v_exp_f32_e32 v116, v116
	s_nop 0
	v_add_f32_e32 v115, 1.0, v115
	v_add_f32_e32 v116, 1.0, v116
	v_rcp_f32_e32 v115, v115
	v_rcp_f32_e32 v116, v116
	s_nop 0
	v_mul_f32_e32 v115, v106, v115
	v_mul_f32_e32 v116, v107, v116
	ds_write_b32 v22, v115 offset:57344
	ds_write_b32 v22, v116 offset:59392
	v_mul_f32_e32 v115, 0xbfb8aa3b, v108
	v_mul_f32_e32 v116, 0xbfb8aa3b, v109
	v_exp_f32_e32 v115, v115
	v_exp_f32_e32 v116, v116
	s_nop 0
	v_add_f32_e32 v115, 1.0, v115
	v_add_f32_e32 v116, 1.0, v116
	v_rcp_f32_e32 v115, v115
	v_rcp_f32_e32 v116, v116
	s_nop 0
	v_mul_f32_e32 v115, v108, v115
	v_mul_f32_e32 v116, v109, v116
	ds_write_b32 v22, v115 offset:61440
	ds_write_b32 v22, v116 offset:63488
	v_mul_f32_e32 v115, 0xbfb8aa3b, v110
	v_mul_f32_e32 v116, 0xbfb8aa3b, v111
	v_exp_f32_e32 v115, v115
	v_exp_f32_e32 v116, v116
	s_nop 0
	v_add_f32_e32 v115, 1.0, v115
	v_add_f32_e32 v116, 1.0, v116
	v_rcp_f32_e32 v115, v115
	v_rcp_f32_e32 v116, v116
	s_nop 0
	v_mul_f32_e32 v115, v110, v115
	v_mul_f32_e32 v116, v111, v116
	ds_write_b32 v114, v115
	ds_write_b32 v114, v116 offset:2048
	v_mul_f32_e32 v115, 0xbfb8aa3b, v112
	v_mul_f32_e32 v116, 0xbfb8aa3b, v113
	v_exp_f32_e32 v115, v115
	v_exp_f32_e32 v116, v116
	s_nop 0
	v_add_f32_e32 v115, 1.0, v115
	v_add_f32_e32 v116, 1.0, v116
	v_rcp_f32_e32 v115, v115
	v_rcp_f32_e32 v116, v116
	s_nop 0
	v_mul_f32_e32 v115, v112, v115
	v_mul_f32_e32 v116, v113, v116
	ds_write_b32 v114, v115 offset:4096
	ds_write_b32 v114, v116 offset:6144
